# N=1024 GEMM phases: workgroups owning a K-split context unit run it first, latent unit second (de-phases the residual epilogue burst); on top of v8
# speedup vs baseline: 1.0064x; 1.0064x over previous
.LBB0_259:
	s_min_u32 s1, s0, 0x800
	s_lshr_b32 s11, s0, 6
	v_cvt_f32_ubyte1_e32 v3, s1
	v_cvt_f32_u32_e32 v2, s11
	v_rcp_iflag_f32_e32 v4, v3
	s_lshr_b32 s49, s1, 8
	v_readlane_b32 s22, v242, 13
	v_readlane_b32 s23, v242, 14
	v_mul_f32_e32 v5, v2, v4
	v_trunc_f32_e32 v5, v5
	v_fma_f32 v2, -v5, v3, v2
	v_cvt_u32_f32_e32 v5, v5
	v_cmp_ge_f32_e64 s[16:17], |v2|, v3
	s_cmp_lg_u64 s[16:17], 0
	v_readlane_b32 s30, v242, 15
	v_readfirstlane_b32 s7, v5
	s_addc_u32 s7, s7, 0
	s_and_b32 s50, s7, 62
	s_mul_i32 s7, s49, s50
	s_sub_i32 s7, s11, s7
	s_sext_i32_i8 s7, s7
	s_ashr_i32 s51, s7, 1
	s_lshr_b32 s1, s1, 4
	s_and_b64 s[16:17], s[42:43], exec
	s_cselect_b32 s27, 0, 0
	s_cselect_b32 s26, s1, 0
	v_readlane_b32 s100, v242, 4
	s_cmp_lt_u32 s100, s26
	s_cselect_b64 s[100:101], -1, 0
	s_and_b32 s16, s100, 0x100
	s_add_u32 s22, s22, s16
	s_addc_u32 s23, s23, 0
	v_mov_b64_e32 v[2:3], s[26:27]
	v_cmp_lt_u64_e32 vcc, s[22:23], v[2:3]
	v_mul_f32_e32 v2, 0x4f7ffffe, v4
	v_cvt_u32_f32_e32 v2, v2
	v_readlane_b32 s31, v242, 16
	s_or_b64 s[30:31], s[30:31], s[100:101]
	s_and_b64 s[28:29], s[30:31], vcc
	s_and_b64 s[16:17], s[28:29], exec
	s_cselect_b32 s1, s22, 0
	s_sub_i32 s17, 0, s49
	v_readfirstlane_b32 s54, v2
	s_mul_i32 s17, s17, s54
	s_mul_hi_u32 s17, s54, s17
	s_abs_i32 s16, s1
	s_add_i32 s54, s54, s17
	s_mul_hi_u32 s17, s16, s54
	s_mul_i32 s22, s17, s49
	s_sub_i32 s16, s16, s22
	s_ashr_i32 s7, s1, 31
	s_add_i32 s22, s17, 1
	s_sub_i32 s23, s16, s49
	s_cmp_ge_u32 s16, s49
	s_cselect_b32 s17, s22, s17
	s_cselect_b32 s16, s23, s16
	s_add_i32 s22, s17, 1
	s_cmp_ge_u32 s16, s49
	s_cselect_b32 s16, s22, s17
	s_xor_b32 s16, s16, s7
	s_sub_i32 s7, s16, s7
	v_mov_b32_e32 v14, v0
	s_mul_i32 s16, s7, s49
	s_mov_b32 s24, 0
	s_sub_i32 s16, s1, s16
	v_readfirstlane_b32 s10, v14
	s_andn2_b64 vcc, exec, s[30:31]
	s_cbranch_vccnz .LBB0_265
	s_cmp_lt_i32 s16, s51
	s_cselect_b64 s[30:31], -1, 0
	s_add_i32 s1, s50, 2
	s_cmp_ge_i32 s16, s51
	s_mov_b64 s[34:35], -1
	s_cbranch_scc0 .LBB0_262
	s_sub_i32 s22, s16, s51
	s_mul_i32 s17, s1, s51
	s_mul_i32 s22, s22, s50
	s_add_i32 s17, s22, s17
	s_mov_b64 s[34:35], 0

.LBB0_266:
	v_bfe_i32 v4, v14, 27, 1
	v_lshlrev_b32_e32 v2, 4, v14
	v_lshrrev_b32_e32 v4, 22, v4
	v_add_u32_e32 v4, v2, v4
	v_and_b32_e32 v4, 0xfffffc00, v4
	v_sub_u32_e32 v4, v2, v4
	v_ashrrev_i32_e32 v3, 31, v14
	v_lshrrev_b32_e32 v5, 4, v4
	v_lshrrev_b32_e32 v3, 26, v3
	v_bitop3_b32 v4, v5, v4, 32 bitop3:0x6c
	v_add_u32_e32 v3, v14, v3
	v_ashrrev_i32_e32 v6, 31, v4
	v_ashrrev_i32_e32 v3, 6, v3
	v_lshrrev_b32_e32 v6, 26, v6
	v_lshlrev_b32_e32 v5, 3, v3
	v_add_u32_e32 v6, v4, v6
	v_lshlrev_b32_e32 v3, 5, v3
	v_and_b32_e32 v5, 0x7ffffff0, v5
	v_ashrrev_i32_e32 v7, 6, v6
	v_and_b32_e32 v15, 32, v3
	v_and_b32_e32 v3, 0xc0, v6
	v_add_u32_e32 v5, v7, v5
	v_sub_u32_e32 v3, v4, v3
	v_ashrrev_i16_sdwa v3, v221, sext(v3) dst_sel:DWORD dst_unused:UNUSED_PAD src0_sel:DWORD src1_sel:BYTE_0
	v_mul_lo_u32 v17, v5, s0
	v_bfe_i32 v16, v3, 0, 16
	v_or_b32_e32 v3, v17, v15
	v_add_u32_e32 v2, 0x2000, v2
	v_add_lshl_u32 v184, v3, v16, 1
	v_ashrrev_i32_e32 v3, 31, v2
	v_lshrrev_b32_e32 v3, 22, v3
	v_add_u32_e32 v3, v2, v3
	v_ashrrev_i32_e32 v3, 10, v3
	v_mul_i32_i24_e32 v4, 0x400, v3
	v_sub_u32_e32 v2, v2, v4
	v_lshrrev_b32_e32 v4, 4, v2
	s_ashr_i32 s17, s10, 6
	s_lshl_b32 s78, s0, 8
	s_ashr_i32 s22, s7, 2
	v_readlane_b32 s2, v242, 11
	s_ashr_i32 s1, s10, 8
	v_bitop3_b32 v2, v4, v2, 32 bitop3:0x6c
	s_lshl_b64 s[66:67], s[78:79], 1
	s_lshl_b32 s56, s17, 10
	s_add_i32 s25, s22, 64
	v_readlane_b32 s3, v242, 12
	s_andn2_b64 s[2:3], s[2:3], s[100:101]
	v_ashrrev_i32_e32 v5, 31, v2
	s_and_b64 s[22:23], s[2:3], exec
	v_lshrrev_b32_e32 v5, 26, v5
	v_readlane_b32 s22, v242, 60
	v_lshlrev_b32_e32 v4, 3, v3
	v_add_u32_e32 v5, v2, v5
	s_cselect_b32 s65, s22, s25
	s_and_b32 s7, s7, 3
	v_and_b32_e32 v4, 0x7ffffff0, v4
	v_ashrrev_i32_e32 v6, 6, v5
	s_and_b64 s[22:23], s[2:3], exec
	v_readlane_b32 s2, v242, 61
	v_add_u32_e32 v4, v6, v4
	s_cselect_b32 s85, s2, s7
	s_ashr_i32 s7, s65, 31
	v_mul_lo_u32 v20, v4, s0
	s_mul_hi_u32 s22, s66, s65
	s_mul_i32 s7, s66, s7
	s_bfe_u32 s0, s0, 0x10017
	s_add_i32 s7, s22, s7
	s_mul_i32 s22, s0, s65
	s_add_i32 s7, s7, s22
	s_mul_i32 s22, s66, s65
	s_add_u32 s25, s36, s22
	s_addc_u32 s7, s37, s7
	s_ashr_i32 s22, s85, 31
	s_mul_hi_u32 s23, s66, s85
	s_mul_i32 s22, s66, s22
	s_add_i32 s22, s23, s22
	s_mul_i32 s0, s0, s85
	s_add_i32 s22, s22, s0
	s_mul_i32 s0, s66, s85
	s_add_u32 s0, s20, s0
	v_lshlrev_b32_e32 v3, 5, v3
	s_addc_u32 s22, s21, s22
	v_and_b32_e32 v18, 32, v3
	v_and_b32_e32 v3, 0xc0, v5
	s_add_u32 s28, s0, s30
	v_sub_u32_e32 v2, v2, v3
	s_addc_u32 s29, s22, s31
	s_add_i32 s63, s56, 0
	v_ashrrev_i16_sdwa v2, v221, sext(v2) dst_sel:DWORD dst_unused:UNUSED_PAD src0_sel:DWORD src1_sel:BYTE_0
	s_add_i32 m0, s63, 0x10000
	v_bfe_i32 v19, v2, 0, 16
	v_or_b32_e32 v2, v20, v18
	global_load_lds_dwordx4 v184, s[28:29]
	s_add_i32 m0, s63, 0x12000
	v_add_lshl_u32 v144, v2, v19, 1
	s_add_u32 s22, s28, s78
	global_load_lds_dwordx4 v144, s[28:29]
	s_addc_u32 s23, s29, 0
	s_add_i32 m0, s63, 0x14000
	v_mov_b32_e32 v145, v185
	global_load_lds_dwordx4 v184, s[22:23]
	s_add_i32 m0, s63, 0x16000
	s_add_u32 s34, s25, s30
	s_addc_u32 s35, s7, s31
	s_add_i32 s55, s63, 0x2000
	v_lshl_add_u64 v[6:7], s[22:23], 0, v[184:185]
	v_lshl_add_u64 v[8:9], s[22:23], 0, v[144:145]
	global_load_lds_dwordx4 v144, s[22:23]
	s_mov_b32 m0, s63
	s_add_u32 s22, s34, s78
	global_load_lds_dwordx4 v184, s[34:35]
	s_mov_b32 m0, s55
	s_addc_u32 s23, s35, 0
	s_add_i32 s82, s63, 0x4000
	global_load_lds_dwordx4 v144, s[34:35]
	s_mov_b32 m0, s82
	s_add_i32 s83, s63, 0x6000
	global_load_lds_dwordx4 v184, s[22:23]
	s_mov_b32 m0, s83
	s_cmp_eq_u32 s1, 1
	global_load_lds_dwordx4 v144, s[22:23]
	v_lshl_add_u64 v[2:3], s[28:29], 0, v[184:185]
	v_lshl_add_u64 v[4:5], s[28:29], 0, v[144:145]
	v_lshl_add_u64 v[10:11], s[34:35], 0, v[184:185]
	v_lshl_add_u64 v[12:13], s[34:35], 0, v[144:145]
	s_cselect_b64 s[76:77], -1, 0
	s_cmp_lg_u32 s1, 1
	v_writelane_b32 v241, s38, 58
	s_cbranch_scc1 .LBB0_268
	s_barrier
.LBB0_268:
	s_lshl_b64 s[4:5], s[4:5], 2
	v_readlane_b32 s0, v241, 43
	s_add_u32 s58, s0, s4
	v_readlane_b32 s0, v241, 44
	s_addc_u32 s92, s0, s5
	v_bfe_u32 v67, v14, 4, 2
	s_add_u32 s93, s74, 0xe400000
	s_waitcnt vmcnt(0)
	v_and_b32_e32 v164, 15, v14
	v_lshlrev_b32_e32 v21, 4, v67
	v_lshlrev_b32_e32 v14, 2, v14
	s_addc_u32 s53, s75, 0
	s_lshl_b32 s0, s1, 6
	v_lshl_or_b32 v21, v164, 6, v21
	s_lshl_b32 s1, s1, 13
	v_and_b32_e32 v14, 32, v14
	v_bitop3_b32 v22, v21, s1, v14 bitop3:0xde
	s_lshl_b32 s1, s17, 5
	s_and_b32 s1, s1, 0x60
	v_readlane_b32 s2, v242, 11
	s_lshl_b32 s4, s1, 7
	v_readlane_b32 s3, v242, 12
	s_andn2_b64 s[2:3], s[2:3], s[100:101]
	v_bitop3_b32 v165, v21, s4, v14 bitop3:0xde
	s_and_b64 s[4:5], s[2:3], exec
	s_cselect_b32 s84, 0, s16
	s_add_i32 m0, s63, 0x18000
	v_lshl_add_u64 v[2:3], v[2:3], 0, s[18:19]
	s_waitcnt vmcnt(2)
	s_barrier
	global_load_lds_dwordx4 v[2:3], off
	v_lshl_add_u64 v[2:3], v[4:5], 0, s[18:19]
	s_add_i32 m0, s63, 0x1a000
	s_add_i32 s23, s63, 0x8000
	global_load_lds_dwordx4 v[2:3], off
	v_lshl_add_u64 v[2:3], v[10:11], 0, s[18:19]
	s_mov_b32 m0, s23
	s_add_i32 s62, s63, 0xa000
	global_load_lds_dwordx4 v[2:3], off
	v_lshl_add_u64 v[2:3], v[12:13], 0, s[18:19]
	s_mov_b32 m0, s62
	s_mov_b32 s7, s6
	global_load_lds_dwordx4 v[2:3], off
	s_add_i32 m0, s63, 0x1c000
	v_lshl_add_u64 v[2:3], v[6:7], 0, s[18:19]
	global_load_lds_dwordx4 v[2:3], off
	v_lshl_add_u64 v[2:3], v[8:9], 0, s[18:19]
	s_add_i32 m0, s63, 0x1e000
	s_cmpk_lt_u32 s10, 0x100
	global_load_lds_dwordx4 v[2:3], off
	v_add_u32_e32 v2, v17, v15
	v_add_lshl_u32 v2, v2, v16, 1
	v_mov_b32_e32 v3, v185
	s_waitcnt vmcnt(6)
	v_lshl_add_u64 v[146:147], s[78:79], 0, v[2:3]
	v_add_u32_e32 v2, v20, v18
	v_add_lshl_u32 v2, v2, v19, 1
	s_mov_b32 s88, s6
	s_mov_b32 s89, s6
	s_mov_b32 s22, 0
	s_cselect_b64 s[94:95], -1, 0
	s_add_i32 s10, s50, 2
	v_lshl_add_u64 v[148:149], s[78:79], 0, v[2:3]
	v_add_u32_e32 v166, 0, v22
	s_barrier
	s_branch .LBB0_271

.LBB0_271:
	s_add_i32 s22, s22, 1
	v_readlane_b32 s2, v242, 6
	s_mul_i32 s4, s22, s48
	s_mul_hi_u32 s5, s22, s2
	s_add_i32 s5, s5, s4
	s_mul_i32 s4, s22, s2
	v_readlane_b32 s2, v242, 4
	s_add_u32 s4, s4, s2
	s_addc_u32 s5, s5, s33
	s_cmp_eq_u32 s22, 1
	s_cselect_b32 s16, s100, 0
	v_readlane_b32 s17, v242, 6
	s_and_b32 s16, s16, s17
	s_sub_u32 s4, s4, s16
	s_subb_u32 s5, s5, 0
	v_cmp_gt_i64_e64 s[40:41], s[4:5], v[186:187]
	s_and_b64 vcc, exec, s[40:41]
	s_mov_b32 s16, 0
	s_mov_b32 s17, 0
	s_cbranch_vccnz .LBB0_277
	s_ashr_i32 s16, s4, 31
	s_lshr_b32 s16, s16, 29
	s_add_i32 s16, s4, s16
	s_and_b32 s17, s16, -8
	s_sub_i32 s17, s4, s17
	s_cmp_gt_i32 s17, -1
	s_mov_b64 s[30:31], -1
	s_cbranch_scc0 .LBB0_274
	s_lshl_b32 s25, s17, 5
	s_mov_b64 s[30:31], 0
